# conv mixer rows in contiguous blocks sized by the workgroup's other phase-4 work (6/6/14 rows per wave)
# speedup vs baseline: 1.0070x; 1.0027x over previous
; __device__ __forceinline__ int ltid() { int t = threadIdx.x; asm volatile("" : "+v"(t)); return t; }
; __device__ __forceinline__ int lbid() { int t = blockIdx.x; asm volatile("" : "+s"(t)); return t; }
; __device__ __forceinline__ void conv_mixer_rows(CArgs a, int layer, int G) {
;     const int lane = ltid() & 63, wave = ltid() >> 6;
;     const int gw = lbid() * NWAVES + wave, NGW = G * NWAVES;
;     const unsigned char* WSB = a->ws;
;     const bf16_t* U = (const bf16_t*)(a->ws + WS_U); bf16_t* Y = (bf16_t*)(a->ws + WS_Y);
;     const float* cw = a->conv_w + (size_t)layer * 3 * 512;
;     const int c0 = lane * 8;
;     float w[3][8];
; #pragma unroll
;     for (int k = 0; k < 3; ++k) { const f32x4 a0 = *(const f32x4*)(cw + k * 512 + c0), a1 = *(const f32x4*)(cw + k * 512 + c0 + 4);
;         w[k][0] = a0[0]; w[k][1] = a0[1]; w[k][2] = a0[2]; w[k][3] = a0[3]; w[k][4] = a1[0]; w[k][5] = a1[1]; w[k][6] = a1[2]; w[k][7] = a1[3]; }
;     auto load = [&](int row, u32x4 (&raw)[7]) {
;         const int s = row & (SEQ - 1);
; #pragma unroll
;         for (int k = 0; k < 3; ++k) {
;             const int sp = s + k - 1; const int rr = (sp >= 0 && sp < SEQ) ? row + k - 1 : row;
;             const bf16_t* ur = U + (size_t)rr * NU;
;             u32x4 h = *(const u32x4*)(ur + UCH + c0), c = *(const u32x4*)(ur + UCC + c0);
;             if (!(sp >= 0 && sp < SEQ)) { h = (u32x4){0u, 0u, 0u, 0u}; c = (u32x4){0u, 0u, 0u, 0u}; }
;             raw[2 * k] = h; raw[2 * k + 1] = c;
;         }
;         raw[6] = *(const u32x4*)(U + (size_t)row * NU + UCB + c0);
;     };
;     ...
;     for (int row = gw; row < T; row += 2 * NGW) {
;         const int row2 = row + NGW;
;         u32x4 ra[7], rb[7];
;         load(row, ra);
;         if (row2 < T) load(row2, rb);
.Lp4_conv_entry:
	s_load_dwordx2 s[60:61], s[6:7], 0xe8
	s_load_dwordx2 s[12:13], s[6:7], 0xa8
	v_readfirstlane_b32 s10, v244
	v_and_b32_e32 v2, 63, v244
	v_lshlrev_b32_e32 v6, 5, v2
	v_lshlrev_b32_e32 v2, 4, v2
	v_add_u32_e32 v3, 0x2000, v2
	v_add_u32_e32 v4, 0x1c00, v2
	v_add_u32_e32 v5, 0xc00, v2
	v_add_u32_e32 v2, 0x1800, v2
	v_readlane_b32 s17, v253, 0
	s_lshr_b32 s10, s10, 6
	s_lshl_b32 s16, s64, 3
	s_movk_i32 s24, 0x4000
	s_lshl_b32 s18, s17, 3
	s_cmp_lg_u32 s64, 0x100
	s_cbranch_scc1 .Lcvm_map
	s_movk_i32 s16, 8
	s_mul_i32 s18, s17, 6
	s_movk_i32 s19, 6
	s_cmp_lt_u32 s17, 0xc0
	s_cbranch_scc1 .Lcvm_cls
	s_sub_u32 s18, s17, 0xc0
	s_mul_i32 s18, s18, 14
	s_add_u32 s18, s18, 0x480
	s_movk_i32 s19, 14
.Lcvm_cls:
	s_add_u32 s24, s18, s19
	s_lshl_b32 s24, s24, 3
	s_lshl_b32 s18, s18, 3
.Lcvm_map:
	s_add_i32 s10, s10, s18
	s_mul_i32 s17, s8, 0x1800
	s_waitcnt lgkmcnt(0)
	s_and_b32 s61, s61, 0xffff
	s_add_u32 s12, s12, s17
	s_addc_u32 s13, s13, 0
	s_cmp_lt_u32 s10, s24
	s_cbranch_scc0 .Lcvm_done
	global_load_dwordx4 v[8:11], v6, s[12:13]
	global_load_dwordx4 v[12:15], v6, s[12:13] offset:16
	global_load_dwordx4 v[16:19], v6, s[12:13] offset:2048
	global_load_dwordx4 v[20:23], v6, s[12:13] offset:2064
	s_add_u32 s12, s12, 0x1000
	s_addc_u32 s13, s13, 0
	global_load_dwordx4 v[24:27], v6, s[12:13]
	global_load_dwordx4 v[28:31], v6, s[12:13] offset:16
	s_mov_b32 s23, 0
	s_and_b32 s21, s10, 0x7ff
	s_mul_i32 s19, s10, 0x2400
	s_add_u32 s19, s19, 0x3a00000
	s_sub_u32 s18, s19, 0x2400
	s_add_u32 s20, s19, 0x2400
	s_cmp_eq_u32 s21, 0
	s_cselect_b32 s18, s19, s18
	s_cmpk_eq_u32 s21, 0x7ff
	s_cselect_b32 s20, s19, s20
	buffer_load_dwordx4 v[32:35], v2, s[60:63], s18 offen
	buffer_load_dwordx4 v[36:39], v3, s[60:63], s18 offen
	buffer_load_dwordx4 v[40:43], v2, s[60:63], s19 offen
	buffer_load_dwordx4 v[44:47], v3, s[60:63], s19 offen
	buffer_load_dwordx4 v[48:51], v4, s[60:63], s19 offen
	buffer_load_dwordx4 v[52:55], v2, s[60:63], s20 offen
	buffer_load_dwordx4 v[56:59], v3, s[60:63], s20 offen
	s_mul_i32 s17, s16, 1
	s_add_i32 s17, s10, s17
	s_cmp_lt_u32 s17, s24
	s_cbranch_scc0 .Lcvm_pfskip_1
	s_and_b32 s21, s17, 0x7ff
	s_mul_i32 s19, s17, 0x2400
	s_add_u32 s19, s19, 0x3a00000
	s_sub_u32 s18, s19, 0x2400
	s_add_u32 s20, s19, 0x2400
	s_cmp_eq_u32 s21, 0
	s_cselect_b32 s18, s19, s18
	s_cmpk_eq_u32 s21, 0x7ff
	s_cselect_b32 s20, s19, s20
	buffer_load_dwordx4 v[60:63], v2, s[60:63], s18 offen
	buffer_load_dwordx4 v[64:67], v3, s[60:63], s18 offen
	buffer_load_dwordx4 v[68:71], v2, s[60:63], s19 offen
	buffer_load_dwordx4 v[72:75], v3, s[60:63], s19 offen
	buffer_load_dwordx4 v[76:79], v4, s[60:63], s19 offen
	buffer_load_dwordx4 v[80:83], v2, s[60:63], s20 offen
	buffer_load_dwordx4 v[84:87], v3, s[60:63], s20 offen
	s_branch .Lcvm_pfdone_1

; __device__ __forceinline__ void conv_mixer_rows(CArgs a, int layer, int G) {
;     ...
;     auto load = [&](int row, u32x4 (&raw)[7]) {
;         const int s = row & (SEQ - 1);
; #pragma unroll
;         for (int k = 0; k < 3; ++k) {
;             const int sp = s + k - 1; const int rr = (sp >= 0 && sp < SEQ) ? row + k - 1 : row;
;             const bf16_t* ur = U + (size_t)rr * NU;
;             u32x4 h = *(const u32x4*)(ur + UCH + c0), c = *(const u32x4*)(ur + UCC + c0);
;             if (!(sp >= 0 && sp < SEQ)) { h = (u32x4){0u, 0u, 0u, 0u}; c = (u32x4){0u, 0u, 0u, 0u}; }
;             raw[2 * k] = h; raw[2 * k + 1] = c;
;         }
;         raw[6] = *(const u32x4*)(U + (size_t)row * NU + UCB + c0);
;     };
;     ...
;     for (int row = gw; row < T; row += 2 * NGW) {
;         const int row2 = row + NGW;
;         u32x4 ra[7], rb[7];
;         load(row, ra);
;         if (row2 < T) load(row2, rb);
.Lcvm_pfdone_1:
	s_mul_i32 s17, s16, 2
	s_add_i32 s17, s10, s17
	s_cmp_lt_u32 s17, s24
	s_cbranch_scc0 .Lcvm_pfskip_2
	s_and_b32 s21, s17, 0x7ff
	s_mul_i32 s19, s17, 0x2400
	s_add_u32 s19, s19, 0x3a00000
	s_sub_u32 s18, s19, 0x2400
	s_add_u32 s20, s19, 0x2400
	s_cmp_eq_u32 s21, 0
	s_cselect_b32 s18, s19, s18
	s_cmpk_eq_u32 s21, 0x7ff
	s_cselect_b32 s20, s19, s20
	buffer_load_dwordx4 v[88:91], v2, s[60:63], s18 offen
	buffer_load_dwordx4 v[92:95], v3, s[60:63], s18 offen
	buffer_load_dwordx4 v[96:99], v2, s[60:63], s19 offen
	buffer_load_dwordx4 v[100:103], v3, s[60:63], s19 offen
	buffer_load_dwordx4 v[104:107], v4, s[60:63], s19 offen
	buffer_load_dwordx4 v[108:111], v2, s[60:63], s20 offen
	buffer_load_dwordx4 v[112:115], v3, s[60:63], s20 offen
	s_branch .Lcvm_pfdone_2

; #define wt16(p, v) wt16b(WSB, (p), (v))
; __device__ __forceinline__ u32x4 pack8(const float (&f)[8]) { u32x4 v; v.x = cvt_pk_bf16(f[0], f[1]); v.y = cvt_pk_bf16(f[2], f[3]); v.z = cvt_pk_bf16(f[4], f[5]); v.w = cvt_pk_bf16(f[6], f[7]); return v; }
; __device__ __forceinline__ void conv_mixer_rows(CArgs a, int layer, int G) {
;     ...
;     auto finish = [&](int row, const u32x4 (&raw)[7]) {
;         float accv[8];
; #pragma unroll
;         for (int e = 0; e < 8; ++e) accv[e] = 0.f;
; #pragma unroll
;         for (int k = 0; k < 3; ++k) { float ch[8], cc[8]; unpack8(raw[2 * k], ch); unpack8(raw[2 * k + 1], cc);
; #pragma unroll
;             for (int e = 0; e < 8; ++e) accv[e] += w[k][e] * (cc[e] * ch[e]); }
;         float cbv[8]; unpack8(raw[6], cbv);
;         float ss = 0.f;
; #pragma unroll
;         for (int e = 0; e < 8; ++e) { accv[e] *= cbv[e]; ss += accv[e] * accv[e]; }
;         ss += __shfl_xor(ss, 1); ss += __shfl_xor(ss, 2); ss += __shfl_xor(ss, 4);
;         const float r = rsqrtf(ss * (1.f / 64.f) + EPS);
; #pragma unroll
;         for (int e = 0; e < 8; ++e) accv[e] *= r;
;         wt16(Y + (size_t)row * 2048 + 1536 + c0, pack8(accv));
;     };
;     for (int row = gw; row < T; row += 2 * NGW) {
;         const int row2 = row + NGW;
;         u32x4 ra[7], rb[7];
;         load(row, ra);
;         if (row2 < T) load(row2, rb);
;         finish(row, ra);
;         if (row2 < T) finish(row2, rb);
;     }
.Lcvm_nz2_1:
	v_lshlrev_b32_e32 v128, 16, v32
	v_and_b32_e32 v129, 0xffff0000, v32
	v_lshlrev_b32_e32 v130, 16, v33
	v_and_b32_e32 v131, 0xffff0000, v33
	v_lshlrev_b32_e32 v132, 16, v34
	v_and_b32_e32 v133, 0xffff0000, v34
	v_lshlrev_b32_e32 v134, 16, v35
	v_and_b32_e32 v135, 0xffff0000, v35
	v_lshlrev_b32_e32 v136, 16, v36
	v_and_b32_e32 v137, 0xffff0000, v36
	v_lshlrev_b32_e32 v138, 16, v37
	v_and_b32_e32 v139, 0xffff0000, v37
	v_lshlrev_b32_e32 v140, 16, v38
	v_and_b32_e32 v141, 0xffff0000, v38
	v_lshlrev_b32_e32 v142, 16, v39
	v_and_b32_e32 v143, 0xffff0000, v39
	v_mul_f32_e32 v128, v136, v128
	v_mul_f32_e32 v129, v137, v129
	v_mul_f32_e32 v130, v138, v130
	v_mul_f32_e32 v131, v139, v131
	v_mul_f32_e32 v132, v140, v132
	v_mul_f32_e32 v133, v141, v133
	v_mul_f32_e32 v134, v142, v134
	v_mul_f32_e32 v135, v143, v135
	v_mul_f32_e32 v120, v8, v128
	v_mul_f32_e32 v121, v9, v129
	v_mul_f32_e32 v122, v10, v130
	v_mul_f32_e32 v123, v11, v131
	v_mul_f32_e32 v124, v12, v132
	v_mul_f32_e32 v125, v13, v133
	v_mul_f32_e32 v126, v14, v134
	v_mul_f32_e32 v127, v15, v135
	v_lshlrev_b32_e32 v128, 16, v40
	v_and_b32_e32 v129, 0xffff0000, v40
	v_lshlrev_b32_e32 v130, 16, v41
	v_and_b32_e32 v131, 0xffff0000, v41
	v_lshlrev_b32_e32 v132, 16, v42
	v_and_b32_e32 v133, 0xffff0000, v42
	v_lshlrev_b32_e32 v134, 16, v43
	v_and_b32_e32 v135, 0xffff0000, v43
	v_lshlrev_b32_e32 v136, 16, v44
	v_and_b32_e32 v137, 0xffff0000, v44
	v_lshlrev_b32_e32 v138, 16, v45
	v_and_b32_e32 v139, 0xffff0000, v45
	v_lshlrev_b32_e32 v140, 16, v46
	v_and_b32_e32 v141, 0xffff0000, v46
	v_lshlrev_b32_e32 v142, 16, v47
	v_and_b32_e32 v143, 0xffff0000, v47
	v_mul_f32_e32 v128, v136, v128
	v_mul_f32_e32 v129, v137, v129
	v_mul_f32_e32 v130, v138, v130
	v_mul_f32_e32 v131, v139, v131
	v_mul_f32_e32 v132, v140, v132
	v_mul_f32_e32 v133, v141, v133
	v_mul_f32_e32 v134, v142, v134
	v_mul_f32_e32 v135, v143, v135
	v_fmac_f32_e32 v120, v16, v128
	v_fmac_f32_e32 v121, v17, v129
	v_fmac_f32_e32 v122, v18, v130
	v_fmac_f32_e32 v123, v19, v131
	v_fmac_f32_e32 v124, v20, v132
	v_fmac_f32_e32 v125, v21, v133
	v_fmac_f32_e32 v126, v22, v134
	v_fmac_f32_e32 v127, v23, v135
	v_lshlrev_b32_e32 v128, 16, v52
	v_and_b32_e32 v129, 0xffff0000, v52
	v_lshlrev_b32_e32 v130, 16, v53
	v_and_b32_e32 v131, 0xffff0000, v53
	v_lshlrev_b32_e32 v132, 16, v54
	v_and_b32_e32 v133, 0xffff0000, v54
	v_lshlrev_b32_e32 v134, 16, v55
	v_and_b32_e32 v135, 0xffff0000, v55
	v_lshlrev_b32_e32 v136, 16, v56
	v_and_b32_e32 v137, 0xffff0000, v56
	v_lshlrev_b32_e32 v138, 16, v57
	v_and_b32_e32 v139, 0xffff0000, v57
	v_lshlrev_b32_e32 v140, 16, v58
	v_and_b32_e32 v141, 0xffff0000, v58
	v_lshlrev_b32_e32 v142, 16, v59
	v_and_b32_e32 v143, 0xffff0000, v59
	v_mul_f32_e32 v128, v136, v128
	v_mul_f32_e32 v129, v137, v129
	v_mul_f32_e32 v130, v138, v130
	v_mul_f32_e32 v131, v139, v131
	v_mul_f32_e32 v132, v140, v132
	v_mul_f32_e32 v133, v141, v133
	v_mul_f32_e32 v134, v142, v134
	v_mul_f32_e32 v135, v143, v135
	v_fmac_f32_e32 v120, v24, v128
	v_fmac_f32_e32 v121, v25, v129
	v_fmac_f32_e32 v122, v26, v130
	v_fmac_f32_e32 v123, v27, v131
	v_fmac_f32_e32 v124, v28, v132
	v_fmac_f32_e32 v125, v29, v133
	v_fmac_f32_e32 v126, v30, v134
	v_fmac_f32_e32 v127, v31, v135
	v_lshlrev_b32_e32 v136, 16, v48
	v_and_b32_e32 v137, 0xffff0000, v48
	v_lshlrev_b32_e32 v138, 16, v49
	v_and_b32_e32 v139, 0xffff0000, v49
	v_lshlrev_b32_e32 v140, 16, v50
	v_and_b32_e32 v141, 0xffff0000, v50
	v_lshlrev_b32_e32 v142, 16, v51
	v_and_b32_e32 v143, 0xffff0000, v51
	v_mul_f32_e32 v120, v120, v136
	v_mul_f32_e32 v121, v121, v137
	v_mul_f32_e32 v122, v122, v138
	v_mul_f32_e32 v123, v123, v139
	v_mul_f32_e32 v124, v124, v140
	v_mul_f32_e32 v125, v125, v141
	v_mul_f32_e32 v126, v126, v142
	v_mul_f32_e32 v127, v127, v143
	v_mul_f32_e32 v144, v120, v120
	v_fmac_f32_e32 v144, v121, v121
	v_fmac_f32_e32 v144, v122, v122
	v_fmac_f32_e32 v144, v123, v123
	v_fmac_f32_e32 v144, v124, v124
	v_fmac_f32_e32 v144, v125, v125
	v_fmac_f32_e32 v144, v126, v126
	v_fmac_f32_e32 v144, v127, v127
	s_nop 1
	v_add_f32_dpp v144, v144, v144 quad_perm:[1,0,3,2] row_mask:0xf bank_mask:0xf
	s_nop 1
	v_add_f32_dpp v144, v144, v144 quad_perm:[2,3,0,1] row_mask:0xf bank_mask:0xf
	s_nop 1
	v_add_f32_dpp v144, v144, v144 row_half_mirror row_mask:0xf bank_mask:0xf
	v_fmamk_f32 v145, v144, 0x3c800000, v245
	v_rsq_f32_e32 v145, v145
	s_lshl_b32 s22, s10, 12
	s_add_u32 s22, s22, 0x10a00000
	v_mul_f32_e32 v120, v120, v145
	v_mul_f32_e32 v121, v121, v145
	v_mul_f32_e32 v122, v122, v145
	v_mul_f32_e32 v123, v123, v145
	v_mul_f32_e32 v124, v124, v145
	v_mul_f32_e32 v125, v125, v145
	v_mul_f32_e32 v126, v126, v145
	v_mul_f32_e32 v127, v127, v145
	v_cvt_pk_bf16_f32 v120, v120, v121
	v_cvt_pk_bf16_f32 v121, v122, v123
	v_cvt_pk_bf16_f32 v122, v124, v125
	v_cvt_pk_bf16_f32 v123, v126, v127
	buffer_store_dwordx4 v[120:123], v5, s[60:63], s22 offen sc1
	s_mul_i32 s17, s16, 3
	s_add_i32 s17, s10, s17
	s_cmp_lt_u32 s17, s24
	s_cbranch_scc0 .Lcvm_pfskip_4
	s_and_b32 s21, s17, 0x7ff
	s_mul_i32 s19, s17, 0x2400
	s_add_u32 s19, s19, 0x3a00000
	s_sub_u32 s18, s19, 0x2400
	s_add_u32 s20, s19, 0x2400
	s_cmp_eq_u32 s21, 0
	s_cselect_b32 s18, s19, s18
	s_cmpk_eq_u32 s21, 0x7ff
	s_cselect_b32 s20, s19, s20
	buffer_load_dwordx4 v[32:35], v2, s[60:63], s18 offen
	buffer_load_dwordx4 v[36:39], v3, s[60:63], s18 offen
	buffer_load_dwordx4 v[40:43], v2, s[60:63], s19 offen
	buffer_load_dwordx4 v[44:47], v3, s[60:63], s19 offen
	buffer_load_dwordx4 v[48:51], v4, s[60:63], s19 offen
	buffer_load_dwordx4 v[52:55], v2, s[60:63], s20 offen
	buffer_load_dwordx4 v[56:59], v3, s[60:63], s20 offen
	s_branch .Lcvm_pfdone_4

; __device__ __forceinline__ void conv_mixer_rows(CArgs a, int layer, int G) {
;     ...
;     for (int row = gw; row < T; row += 2 * NGW) {
;         const int row2 = row + NGW;
;         u32x4 ra[7], rb[7];
;         load(row, ra);
;         if (row2 < T) load(row2, rb);
;         finish(row, ra);
;         if (row2 < T) finish(row2, rb);
;     }
.Lcvm_pfdone_4:
	s_add_i32 s10, s10, s16
	s_cmp_lt_u32 s10, s24
	s_cbranch_scc0 .Lcvm_done
	s_cmp_eq_u32 s23, 0
	s_cbranch_scc1 .Lcvm_wc_5
	s_waitcnt vmcnt(0)
	s_branch .Lcvm_wg_5

; #define wt16(p, v) wt16b(WSB, (p), (v))
; __device__ __forceinline__ u32x4 pack8(const float (&f)[8]) { u32x4 v; v.x = cvt_pk_bf16(f[0], f[1]); v.y = cvt_pk_bf16(f[2], f[3]); v.z = cvt_pk_bf16(f[4], f[5]); v.w = cvt_pk_bf16(f[6], f[7]); return v; }
; __device__ __forceinline__ void conv_mixer_rows(CArgs a, int layer, int G) {
;     ...
;     auto finish = [&](int row, const u32x4 (&raw)[7]) {
;         float accv[8];
; #pragma unroll
;         for (int e = 0; e < 8; ++e) accv[e] = 0.f;
; #pragma unroll
;         for (int k = 0; k < 3; ++k) { float ch[8], cc[8]; unpack8(raw[2 * k], ch); unpack8(raw[2 * k + 1], cc);
; #pragma unroll
;             for (int e = 0; e < 8; ++e) accv[e] += w[k][e] * (cc[e] * ch[e]); }
;         float cbv[8]; unpack8(raw[6], cbv);
;         float ss = 0.f;
; #pragma unroll
;         for (int e = 0; e < 8; ++e) { accv[e] *= cbv[e]; ss += accv[e] * accv[e]; }
;         ss += __shfl_xor(ss, 1); ss += __shfl_xor(ss, 2); ss += __shfl_xor(ss, 4);
;         const float r = rsqrtf(ss * (1.f / 64.f) + EPS);
; #pragma unroll
;         for (int e = 0; e < 8; ++e) accv[e] *= r;
;         wt16(Y + (size_t)row * 2048 + 1536 + c0, pack8(accv));
;     };
;     for (int row = gw; row < T; row += 2 * NGW) {
;         const int row2 = row + NGW;
;         u32x4 ra[7], rb[7];
;         load(row, ra);
;         if (row2 < T) load(row2, rb);
;         finish(row, ra);
;         if (row2 < T) finish(row2, rb);
;     }
.Lcvm_nz2_2:
	v_lshlrev_b32_e32 v128, 16, v60
	v_and_b32_e32 v129, 0xffff0000, v60
	v_lshlrev_b32_e32 v130, 16, v61
	v_and_b32_e32 v131, 0xffff0000, v61
	v_lshlrev_b32_e32 v132, 16, v62
	v_and_b32_e32 v133, 0xffff0000, v62
	v_lshlrev_b32_e32 v134, 16, v63
	v_and_b32_e32 v135, 0xffff0000, v63
	v_lshlrev_b32_e32 v136, 16, v64
	v_and_b32_e32 v137, 0xffff0000, v64
	v_lshlrev_b32_e32 v138, 16, v65
	v_and_b32_e32 v139, 0xffff0000, v65
	v_lshlrev_b32_e32 v140, 16, v66
	v_and_b32_e32 v141, 0xffff0000, v66
	v_lshlrev_b32_e32 v142, 16, v67
	v_and_b32_e32 v143, 0xffff0000, v67
	v_mul_f32_e32 v128, v136, v128
	v_mul_f32_e32 v129, v137, v129
	v_mul_f32_e32 v130, v138, v130
	v_mul_f32_e32 v131, v139, v131
	v_mul_f32_e32 v132, v140, v132
	v_mul_f32_e32 v133, v141, v133
	v_mul_f32_e32 v134, v142, v134
	v_mul_f32_e32 v135, v143, v135
	v_mul_f32_e32 v120, v8, v128
	v_mul_f32_e32 v121, v9, v129
	v_mul_f32_e32 v122, v10, v130
	v_mul_f32_e32 v123, v11, v131
	v_mul_f32_e32 v124, v12, v132
	v_mul_f32_e32 v125, v13, v133
	v_mul_f32_e32 v126, v14, v134
	v_mul_f32_e32 v127, v15, v135
	v_lshlrev_b32_e32 v128, 16, v68
	v_and_b32_e32 v129, 0xffff0000, v68
	v_lshlrev_b32_e32 v130, 16, v69
	v_and_b32_e32 v131, 0xffff0000, v69
	v_lshlrev_b32_e32 v132, 16, v70
	v_and_b32_e32 v133, 0xffff0000, v70
	v_lshlrev_b32_e32 v134, 16, v71
	v_and_b32_e32 v135, 0xffff0000, v71
	v_lshlrev_b32_e32 v136, 16, v72
	v_and_b32_e32 v137, 0xffff0000, v72
	v_lshlrev_b32_e32 v138, 16, v73
	v_and_b32_e32 v139, 0xffff0000, v73
	v_lshlrev_b32_e32 v140, 16, v74
	v_and_b32_e32 v141, 0xffff0000, v74
	v_lshlrev_b32_e32 v142, 16, v75
	v_and_b32_e32 v143, 0xffff0000, v75
	v_mul_f32_e32 v128, v136, v128
	v_mul_f32_e32 v129, v137, v129
	v_mul_f32_e32 v130, v138, v130
	v_mul_f32_e32 v131, v139, v131
	v_mul_f32_e32 v132, v140, v132
	v_mul_f32_e32 v133, v141, v133
	v_mul_f32_e32 v134, v142, v134
	v_mul_f32_e32 v135, v143, v135
	v_fmac_f32_e32 v120, v16, v128
	v_fmac_f32_e32 v121, v17, v129
	v_fmac_f32_e32 v122, v18, v130
	v_fmac_f32_e32 v123, v19, v131
	v_fmac_f32_e32 v124, v20, v132
	v_fmac_f32_e32 v125, v21, v133
	v_fmac_f32_e32 v126, v22, v134
	v_fmac_f32_e32 v127, v23, v135
	v_lshlrev_b32_e32 v128, 16, v80
	v_and_b32_e32 v129, 0xffff0000, v80
	v_lshlrev_b32_e32 v130, 16, v81
	v_and_b32_e32 v131, 0xffff0000, v81
	v_lshlrev_b32_e32 v132, 16, v82
	v_and_b32_e32 v133, 0xffff0000, v82
	v_lshlrev_b32_e32 v134, 16, v83
	v_and_b32_e32 v135, 0xffff0000, v83
	v_lshlrev_b32_e32 v136, 16, v84
	v_and_b32_e32 v137, 0xffff0000, v84
	v_lshlrev_b32_e32 v138, 16, v85
	v_and_b32_e32 v139, 0xffff0000, v85
	v_lshlrev_b32_e32 v140, 16, v86
	v_and_b32_e32 v141, 0xffff0000, v86
	v_lshlrev_b32_e32 v142, 16, v87
	v_and_b32_e32 v143, 0xffff0000, v87
	v_mul_f32_e32 v128, v136, v128
	v_mul_f32_e32 v129, v137, v129
	v_mul_f32_e32 v130, v138, v130
	v_mul_f32_e32 v131, v139, v131
	v_mul_f32_e32 v132, v140, v132
	v_mul_f32_e32 v133, v141, v133
	v_mul_f32_e32 v134, v142, v134
	v_mul_f32_e32 v135, v143, v135
	v_fmac_f32_e32 v120, v24, v128
	v_fmac_f32_e32 v121, v25, v129
	v_fmac_f32_e32 v122, v26, v130
	v_fmac_f32_e32 v123, v27, v131
	v_fmac_f32_e32 v124, v28, v132
	v_fmac_f32_e32 v125, v29, v133
	v_fmac_f32_e32 v126, v30, v134
	v_fmac_f32_e32 v127, v31, v135
	v_lshlrev_b32_e32 v136, 16, v76
	v_and_b32_e32 v137, 0xffff0000, v76
	v_lshlrev_b32_e32 v138, 16, v77
	v_and_b32_e32 v139, 0xffff0000, v77
	v_lshlrev_b32_e32 v140, 16, v78
	v_and_b32_e32 v141, 0xffff0000, v78
	v_lshlrev_b32_e32 v142, 16, v79
	v_and_b32_e32 v143, 0xffff0000, v79
	v_mul_f32_e32 v120, v120, v136
	v_mul_f32_e32 v121, v121, v137
	v_mul_f32_e32 v122, v122, v138
	v_mul_f32_e32 v123, v123, v139
	v_mul_f32_e32 v124, v124, v140
	v_mul_f32_e32 v125, v125, v141
	v_mul_f32_e32 v126, v126, v142
	v_mul_f32_e32 v127, v127, v143
	v_mul_f32_e32 v144, v120, v120
	v_fmac_f32_e32 v144, v121, v121
	v_fmac_f32_e32 v144, v122, v122
	v_fmac_f32_e32 v144, v123, v123
	v_fmac_f32_e32 v144, v124, v124
	v_fmac_f32_e32 v144, v125, v125
	v_fmac_f32_e32 v144, v126, v126
	v_fmac_f32_e32 v144, v127, v127
	s_nop 1
	v_add_f32_dpp v144, v144, v144 quad_perm:[1,0,3,2] row_mask:0xf bank_mask:0xf
	s_nop 1
	v_add_f32_dpp v144, v144, v144 quad_perm:[2,3,0,1] row_mask:0xf bank_mask:0xf
	s_nop 1
	v_add_f32_dpp v144, v144, v144 row_half_mirror row_mask:0xf bank_mask:0xf
	v_fmamk_f32 v145, v144, 0x3c800000, v245
	v_rsq_f32_e32 v145, v145
	s_lshl_b32 s22, s10, 12
	s_add_u32 s22, s22, 0x10a00000
	v_mul_f32_e32 v120, v120, v145
	v_mul_f32_e32 v121, v121, v145
	v_mul_f32_e32 v122, v122, v145
	v_mul_f32_e32 v123, v123, v145
	v_mul_f32_e32 v124, v124, v145
	v_mul_f32_e32 v125, v125, v145
	v_mul_f32_e32 v126, v126, v145
	v_mul_f32_e32 v127, v127, v145
	v_cvt_pk_bf16_f32 v120, v120, v121
	v_cvt_pk_bf16_f32 v121, v122, v123
	v_cvt_pk_bf16_f32 v122, v124, v125
	v_cvt_pk_bf16_f32 v123, v126, v127
	buffer_store_dwordx4 v[120:123], v5, s[60:63], s22 offen sc1
	s_mul_i32 s17, s16, 3
	s_add_i32 s17, s10, s17
	s_cmp_lt_u32 s17, s24
	s_cbranch_scc0 .Lcvm_pfskip_6
	s_and_b32 s21, s17, 0x7ff
	s_mul_i32 s19, s17, 0x2400
	s_add_u32 s19, s19, 0x3a00000
	s_sub_u32 s18, s19, 0x2400
	s_add_u32 s20, s19, 0x2400
	s_cmp_eq_u32 s21, 0
	s_cselect_b32 s18, s19, s18
	s_cmpk_eq_u32 s21, 0x7ff
	s_cselect_b32 s20, s19, s20
	buffer_load_dwordx4 v[60:63], v2, s[60:63], s18 offen
	buffer_load_dwordx4 v[64:67], v3, s[60:63], s18 offen
	buffer_load_dwordx4 v[68:71], v2, s[60:63], s19 offen
	buffer_load_dwordx4 v[72:75], v3, s[60:63], s19 offen
	buffer_load_dwordx4 v[76:79], v4, s[60:63], s19 offen
	buffer_load_dwordx4 v[80:83], v2, s[60:63], s20 offen
	buffer_load_dwordx4 v[84:87], v3, s[60:63], s20 offen
	s_branch .Lcvm_pfdone_6

; #define wt16(p, v) wt16b(WSB, (p), (v))
; __device__ __forceinline__ u32x4 pack8(const float (&f)[8]) { u32x4 v; v.x = cvt_pk_bf16(f[0], f[1]); v.y = cvt_pk_bf16(f[2], f[3]); v.z = cvt_pk_bf16(f[4], f[5]); v.w = cvt_pk_bf16(f[6], f[7]); return v; }
; __device__ __forceinline__ void conv_mixer_rows(CArgs a, int layer, int G) {
;     ...
;     auto finish = [&](int row, const u32x4 (&raw)[7]) {
;         float accv[8];
; #pragma unroll
;         for (int e = 0; e < 8; ++e) accv[e] = 0.f;
; #pragma unroll
;         for (int k = 0; k < 3; ++k) { float ch[8], cc[8]; unpack8(raw[2 * k], ch); unpack8(raw[2 * k + 1], cc);
; #pragma unroll
;             for (int e = 0; e < 8; ++e) accv[e] += w[k][e] * (cc[e] * ch[e]); }
;         float cbv[8]; unpack8(raw[6], cbv);
;         float ss = 0.f;
; #pragma unroll
;         for (int e = 0; e < 8; ++e) { accv[e] *= cbv[e]; ss += accv[e] * accv[e]; }
;         ss += __shfl_xor(ss, 1); ss += __shfl_xor(ss, 2); ss += __shfl_xor(ss, 4);
;         const float r = rsqrtf(ss * (1.f / 64.f) + EPS);
; #pragma unroll
;         for (int e = 0; e < 8; ++e) accv[e] *= r;
;         wt16(Y + (size_t)row * 2048 + 1536 + c0, pack8(accv));
;     };
;     for (int row = gw; row < T; row += 2 * NGW) {
;         const int row2 = row + NGW;
;         u32x4 ra[7], rb[7];
;         load(row, ra);
;         if (row2 < T) load(row2, rb);
;         finish(row, ra);
;         if (row2 < T) finish(row2, rb);
;     }
.Lcvm_nz2_3:
	v_lshlrev_b32_e32 v128, 16, v88
	v_and_b32_e32 v129, 0xffff0000, v88
	v_lshlrev_b32_e32 v130, 16, v89
	v_and_b32_e32 v131, 0xffff0000, v89
	v_lshlrev_b32_e32 v132, 16, v90
	v_and_b32_e32 v133, 0xffff0000, v90
	v_lshlrev_b32_e32 v134, 16, v91
	v_and_b32_e32 v135, 0xffff0000, v91
	v_lshlrev_b32_e32 v136, 16, v92
	v_and_b32_e32 v137, 0xffff0000, v92
	v_lshlrev_b32_e32 v138, 16, v93
	v_and_b32_e32 v139, 0xffff0000, v93
	v_lshlrev_b32_e32 v140, 16, v94
	v_and_b32_e32 v141, 0xffff0000, v94
	v_lshlrev_b32_e32 v142, 16, v95
	v_and_b32_e32 v143, 0xffff0000, v95
	v_mul_f32_e32 v128, v136, v128
	v_mul_f32_e32 v129, v137, v129
	v_mul_f32_e32 v130, v138, v130
	v_mul_f32_e32 v131, v139, v131
	v_mul_f32_e32 v132, v140, v132
	v_mul_f32_e32 v133, v141, v133
	v_mul_f32_e32 v134, v142, v134
	v_mul_f32_e32 v135, v143, v135
	v_mul_f32_e32 v120, v8, v128
	v_mul_f32_e32 v121, v9, v129
	v_mul_f32_e32 v122, v10, v130
	v_mul_f32_e32 v123, v11, v131
	v_mul_f32_e32 v124, v12, v132
	v_mul_f32_e32 v125, v13, v133
	v_mul_f32_e32 v126, v14, v134
	v_mul_f32_e32 v127, v15, v135
	v_lshlrev_b32_e32 v128, 16, v96
	v_and_b32_e32 v129, 0xffff0000, v96
	v_lshlrev_b32_e32 v130, 16, v97
	v_and_b32_e32 v131, 0xffff0000, v97
	v_lshlrev_b32_e32 v132, 16, v98
	v_and_b32_e32 v133, 0xffff0000, v98
	v_lshlrev_b32_e32 v134, 16, v99
	v_and_b32_e32 v135, 0xffff0000, v99
	v_lshlrev_b32_e32 v136, 16, v100
	v_and_b32_e32 v137, 0xffff0000, v100
	v_lshlrev_b32_e32 v138, 16, v101
	v_and_b32_e32 v139, 0xffff0000, v101
	v_lshlrev_b32_e32 v140, 16, v102
	v_and_b32_e32 v141, 0xffff0000, v102
	v_lshlrev_b32_e32 v142, 16, v103
	v_and_b32_e32 v143, 0xffff0000, v103
	v_mul_f32_e32 v128, v136, v128
	v_mul_f32_e32 v129, v137, v129
	v_mul_f32_e32 v130, v138, v130
	v_mul_f32_e32 v131, v139, v131
	v_mul_f32_e32 v132, v140, v132
	v_mul_f32_e32 v133, v141, v133
	v_mul_f32_e32 v134, v142, v134
	v_mul_f32_e32 v135, v143, v135
	v_fmac_f32_e32 v120, v16, v128
	v_fmac_f32_e32 v121, v17, v129
	v_fmac_f32_e32 v122, v18, v130
	v_fmac_f32_e32 v123, v19, v131
	v_fmac_f32_e32 v124, v20, v132
	v_fmac_f32_e32 v125, v21, v133
	v_fmac_f32_e32 v126, v22, v134
	v_fmac_f32_e32 v127, v23, v135
	v_lshlrev_b32_e32 v128, 16, v108
	v_and_b32_e32 v129, 0xffff0000, v108
	v_lshlrev_b32_e32 v130, 16, v109
	v_and_b32_e32 v131, 0xffff0000, v109
	v_lshlrev_b32_e32 v132, 16, v110
	v_and_b32_e32 v133, 0xffff0000, v110
	v_lshlrev_b32_e32 v134, 16, v111
	v_and_b32_e32 v135, 0xffff0000, v111
	v_lshlrev_b32_e32 v136, 16, v112
	v_and_b32_e32 v137, 0xffff0000, v112
	v_lshlrev_b32_e32 v138, 16, v113
	v_and_b32_e32 v139, 0xffff0000, v113
	v_lshlrev_b32_e32 v140, 16, v114
	v_and_b32_e32 v141, 0xffff0000, v114
	v_lshlrev_b32_e32 v142, 16, v115
	v_and_b32_e32 v143, 0xffff0000, v115
	v_mul_f32_e32 v128, v136, v128
	v_mul_f32_e32 v129, v137, v129
	v_mul_f32_e32 v130, v138, v130
	v_mul_f32_e32 v131, v139, v131
	v_mul_f32_e32 v132, v140, v132
	v_mul_f32_e32 v133, v141, v133
	v_mul_f32_e32 v134, v142, v134
	v_mul_f32_e32 v135, v143, v135
	v_fmac_f32_e32 v120, v24, v128
	v_fmac_f32_e32 v121, v25, v129
	v_fmac_f32_e32 v122, v26, v130
	v_fmac_f32_e32 v123, v27, v131
	v_fmac_f32_e32 v124, v28, v132
	v_fmac_f32_e32 v125, v29, v133
	v_fmac_f32_e32 v126, v30, v134
	v_fmac_f32_e32 v127, v31, v135
	v_lshlrev_b32_e32 v136, 16, v104
	v_and_b32_e32 v137, 0xffff0000, v104
	v_lshlrev_b32_e32 v138, 16, v105
	v_and_b32_e32 v139, 0xffff0000, v105
	v_lshlrev_b32_e32 v140, 16, v106
	v_and_b32_e32 v141, 0xffff0000, v106
	v_lshlrev_b32_e32 v142, 16, v107
	v_and_b32_e32 v143, 0xffff0000, v107
	v_mul_f32_e32 v120, v120, v136
	v_mul_f32_e32 v121, v121, v137
	v_mul_f32_e32 v122, v122, v138
	v_mul_f32_e32 v123, v123, v139
	v_mul_f32_e32 v124, v124, v140
	v_mul_f32_e32 v125, v125, v141
	v_mul_f32_e32 v126, v126, v142
	v_mul_f32_e32 v127, v127, v143
	v_mul_f32_e32 v144, v120, v120
	v_fmac_f32_e32 v144, v121, v121
	v_fmac_f32_e32 v144, v122, v122
	v_fmac_f32_e32 v144, v123, v123
	v_fmac_f32_e32 v144, v124, v124
	v_fmac_f32_e32 v144, v125, v125
	v_fmac_f32_e32 v144, v126, v126
	v_fmac_f32_e32 v144, v127, v127
	s_nop 1
	v_add_f32_dpp v144, v144, v144 quad_perm:[1,0,3,2] row_mask:0xf bank_mask:0xf
	s_nop 1
	v_add_f32_dpp v144, v144, v144 quad_perm:[2,3,0,1] row_mask:0xf bank_mask:0xf
	s_nop 1
	v_add_f32_dpp v144, v144, v144 row_half_mirror row_mask:0xf bank_mask:0xf
	v_fmamk_f32 v145, v144, 0x3c800000, v245
	v_rsq_f32_e32 v145, v145
	s_lshl_b32 s22, s10, 12
	s_add_u32 s22, s22, 0x10a00000
	v_mul_f32_e32 v120, v120, v145
	v_mul_f32_e32 v121, v121, v145
	v_mul_f32_e32 v122, v122, v145
	v_mul_f32_e32 v123, v123, v145
	v_mul_f32_e32 v124, v124, v145
	v_mul_f32_e32 v125, v125, v145
	v_mul_f32_e32 v126, v126, v145
	v_mul_f32_e32 v127, v127, v145
	v_cvt_pk_bf16_f32 v120, v120, v121
	v_cvt_pk_bf16_f32 v121, v122, v123
	v_cvt_pk_bf16_f32 v122, v124, v125
	v_cvt_pk_bf16_f32 v123, v126, v127
	buffer_store_dwordx4 v[120:123], v5, s[60:63], s22 offen sc1
	s_mul_i32 s17, s16, 3
	s_add_i32 s17, s10, s17
	s_cmp_lt_u32 s17, s24
	s_cbranch_scc0 .Lcvm_pfskip_8
	s_and_b32 s21, s17, 0x7ff
	s_mul_i32 s19, s17, 0x2400
	s_add_u32 s19, s19, 0x3a00000
	s_sub_u32 s18, s19, 0x2400
	s_add_u32 s20, s19, 0x2400
	s_cmp_eq_u32 s21, 0
	s_cselect_b32 s18, s19, s18
	s_cmpk_eq_u32 s21, 0x7ff
	s_cselect_b32 s20, s19, s20
	buffer_load_dwordx4 v[88:91], v2, s[60:63], s18 offen
	buffer_load_dwordx4 v[92:95], v3, s[60:63], s18 offen
	buffer_load_dwordx4 v[96:99], v2, s[60:63], s19 offen
	buffer_load_dwordx4 v[100:103], v3, s[60:63], s19 offen
	buffer_load_dwordx4 v[104:107], v4, s[60:63], s19 offen
	buffer_load_dwordx4 v[108:111], v2, s[60:63], s20 offen
	buffer_load_dwordx4 v[112:115], v3, s[60:63], s20 offen
	s_branch .Lcvm_pfdone_8

; __device__ __forceinline__ void conv_mixer_rows(CArgs a, int layer, int G) {
;     ...
;     for (int row = gw; row < T; row += 2 * NGW) {
;         const int row2 = row + NGW;
;         u32x4 ra[7], rb[7];
;         load(row, ra);
;         if (row2 < T) load(row2, rb);
;         finish(row, ra);
;         if (row2 < T) finish(row2, rb);
;     }
.Lcvm_pfdone_8:
	s_add_i32 s10, s10, s16
	s_cmp_lt_u32 s10, s24
	s_cbranch_scc0 .Lcvm_done

; __device__ __forceinline__ void conv_mixer_rows(CArgs a, int layer, int G) {
;     ...
;     for (int row = gw; row < T; row += 2 * NGW) {
;         const int row2 = row + NGW;
;         u32x4 ra[7], rb[7];
;         load(row, ra);
;         if (row2 < T) load(row2, rb);
;         finish(row, ra);
;         if (row2 < T) finish(row2, rb);
;     }
.Lcvm_pfdone_14:
	s_add_i32 s10, s10, s16
	s_cmp_lt_u32 s10, s24
	s_cbranch_scc0 .Lcvm_done
	s_branch .Lcvm_loop
